# attention QK: score tiles stay in registers until all 16 are done, freeing a 4th 4KiB K buffer (prefetch depth 4)
# speedup vs baseline: 1.0631x; 1.0065x over previous
.Lau_entry:
	v_and_b32_e32 v3, 63, v0
	v_lshrrev_b32_e32 v4, 6, v0
	v_readfirstlane_b32 s75, v138
	v_and_b32_e32 v1, 15, v3
	v_readfirstlane_b32 s76, v4
	v_lshrrev_b32_e32 v2, 4, v3
	s_lshl_b32 s76, s76, 11
	s_add_i32 s76, s76, 0x24000
	v_lshl_add_u32 v4, v2, 2, v138
	ds_read2_b32 v[10:11], v4 offset0:0 offset1:4
	ds_read2_b32 v[12:13], v4 offset0:8 offset1:12
	ds_read2_b32 v[14:15], v4 offset0:16 offset1:20
	ds_read2_b32 v[16:17], v4 offset0:24 offset1:28
	ds_read2_b32 v[18:19], v4 offset0:32 offset1:36
	ds_read2_b32 v[20:21], v4 offset0:40 offset1:44
	ds_read2_b32 v[22:23], v4 offset0:48 offset1:52
	ds_read2_b32 v[24:25], v4 offset0:56 offset1:60
	ds_read2_b32 v[26:27], v4 offset0:64 offset1:68
	ds_read2_b32 v[28:29], v4 offset0:72 offset1:76
	ds_read2_b32 v[30:31], v4 offset0:80 offset1:84
	ds_read2_b32 v[32:33], v4 offset0:88 offset1:92
	ds_read2_b32 v[34:35], v4 offset0:96 offset1:100
	ds_read2_b32 v[36:37], v4 offset0:104 offset1:108
	ds_read2_b32 v[38:39], v4 offset0:112 offset1:116
	ds_read2_b32 v[40:41], v4 offset0:120 offset1:124
	ds_read2_b32 v[42:43], v4 offset0:128 offset1:132
	ds_read2_b32 v[44:45], v4 offset0:136 offset1:140
	ds_read2_b32 v[46:47], v4 offset0:144 offset1:148
	ds_read2_b32 v[48:49], v4 offset0:152 offset1:156
	ds_read2_b32 v[50:51], v4 offset0:160 offset1:164
	ds_read2_b32 v[52:53], v4 offset0:168 offset1:172
	ds_read2_b32 v[54:55], v4 offset0:176 offset1:180
	ds_read2_b32 v[56:57], v4 offset0:184 offset1:188
	ds_read2_b32 v[58:59], v4 offset0:192 offset1:196
	ds_read2_b32 v[60:61], v4 offset0:200 offset1:204
	ds_read2_b32 v[62:63], v4 offset0:208 offset1:212
	ds_read2_b32 v[64:65], v4 offset0:216 offset1:220
	ds_read2_b32 v[66:67], v4 offset0:224 offset1:228
	ds_read2_b32 v[68:69], v4 offset0:232 offset1:236
	ds_read2_b32 v[70:71], v4 offset0:240 offset1:244
	ds_read2_b32 v[72:73], v4 offset0:248 offset1:252
	v_readlane_b32 s40, v251, 27
	v_readlane_b32 s41, v251, 28
	v_readlane_b32 s42, v251, 29
	v_readlane_b32 s43, v251, 30
	v_readlane_b32 s44, v251, 31
	v_readlane_b32 s45, v251, 32
	v_readlane_b32 s46, v251, 49
	v_readlane_b32 s47, v251, 50
	s_lshl_b32 s8, s70, 11
	s_lshl_b32 s9, s72, 9
	s_add_u32 s56, s40, s8
	s_addc_u32 s57, s41, 0
	s_add_u32 s50, s42, s9
	s_addc_u32 s51, s43, 0
	s_add_u32 s52, s44, s9
	s_addc_u32 s53, s45, 0
	s_add_u32 s58, s46, s8
	s_addc_u32 s59, s47, 0
	v_lshlrev_b32_e32 v5, 1, v2
	v_xor_b32_e32 v5, v1, v5
	v_lshlrev_b32_e32 v5, 4, v5
	v_xor_b32_e32 v6, 0x80, v5
	v_and_b32_e32 v7, 3, v1
	v_and_b32_e32 v8, 8, v1
	v_lshl_or_b32 v8, v7, 1, v8
	v_or_b32_e32 v9, 0, v2
	v_xor_b32_e32 v9, v9, v8
	v_lshlrev_b32_e32 v9, 4, v9
	v_lshl_add_u32 v9, v1, 8, v9
	v_add_u32_e32 v74, s75, v9
	v_or_b32_e32 v9, 4, v2
	v_xor_b32_e32 v9, v9, v8
	v_lshlrev_b32_e32 v9, 4, v9
	v_lshl_add_u32 v9, v1, 8, v9
	v_add_u32_e32 v75, s75, v9
	v_or_b32_e32 v9, 8, v2
	v_xor_b32_e32 v9, v9, v8
	v_lshlrev_b32_e32 v9, 4, v9
	v_lshl_add_u32 v9, v1, 8, v9
	v_add_u32_e32 v76, s75, v9
	v_or_b32_e32 v9, 12, v2
	v_xor_b32_e32 v9, v9, v8
	v_lshlrev_b32_e32 v9, 4, v9
	v_lshl_add_u32 v9, v1, 8, v9
	v_add_u32_e32 v77, s75, v9
	v_lshrrev_b32_e32 v128, 2, v1
	v_lshl_or_b32 v129, v2, 3, v128
	v_and_b32_e32 v130, 1, v2
	v_lshl_or_b32 v130, v130, 2, v128
	v_lshlrev_b32_e32 v129, 8, v129
	v_lshl_add_u32 v129, v7, 3, v129
	v_add_u32_e32 v129, s75, v129
	v_xor_b32_e32 v9, 0, v130
	v_lshl_add_u32 v78, v9, 5, v129
	v_xor_b32_e32 v9, 1, v130
	v_lshl_add_u32 v79, v9, 5, v129
	v_xor_b32_e32 v9, 2, v130
	v_lshl_add_u32 v80, v9, 5, v129
	v_xor_b32_e32 v9, 3, v130
	v_lshl_add_u32 v81, v9, 5, v129
	v_xor_b32_e32 v9, 4, v130
	v_lshl_add_u32 v82, v9, 5, v129
	v_xor_b32_e32 v9, 5, v130
	v_lshl_add_u32 v83, v9, 5, v129
	v_xor_b32_e32 v9, 6, v130
	v_lshl_add_u32 v84, v9, 5, v129
	v_xor_b32_e32 v9, 7, v130
	v_lshl_add_u32 v85, v9, 5, v129
	v_lshl_add_u32 v86, v1, 4, s75
	v_lshl_add_u32 v87, v3, 4, s75
	v_lshl_add_u32 v88, v3, 1, s76
	v_cmp_gt_u32_e64 s[20:21], 4, v1
	v_lshlrev_b32_e32 v9, 4, v2
	v_lshl_add_u32 v128, v7, 9, v9
	v_add_u32_e32 v128, s76, v128
	v_add_u32_e32 v131, 0x22000, v9
	v_cndmask_b32_e64 v89, v131, v128, s[20:21]
	v_lshrrev_b32_e32 v128, 3, v1
	v_add_u32_e32 v128, v128, v1
	v_lshl_add_u32 v132, v128, 4, s75
	v_add_u32_e32 v132, 0x400, v132
	v_and_b32_e32 v128, 3, v3
	v_lshrrev_b32_e32 v129, 2, v3
	v_mul_u32_u24_e32 v131, 0x90, v129
	v_lshl_add_u32 v131, v128, 2, v131
	v_add_u32_e32 v133, s75, v131
	v_add_u32_e32 v133, 0x400, v133
	v_lshlrev_b32_e32 v129, 4, v129
	v_lshl_add_u32 v90, v128, 8, v129
	v_lshl_add_u32 v91, v7, 8, v9
	v_mov_b32_e32 v128, 0
	v_mov_b32_e32 v129, 0
	v_lshlrev_b32_e32 v9, 3, v3
	v_add_u32_e32 v9, 0x22000, v9
	ds_write_b64 v9, v[128:129]
	v_cmp_gt_u32_e64 s[24:25], s73, v3
	v_add_u32_e32 v9, 64, v3
	v_cmp_gt_u32_e64 s[26:27], s73, v9
	v_add_u32_e32 v9, 0x80, v3
	v_cmp_gt_u32_e64 s[28:29], s73, v9
	v_add_u32_e32 v9, 0xc0, v3
	v_cmp_gt_u32_e64 s[30:31], s73, v9
	s_waitcnt lgkmcnt(0)
	v_lshl_add_u32 v10, v10, 9, v5
	v_lshl_add_u32 v11, v11, 9, v5
	v_lshl_add_u32 v12, v12, 9, v6
	v_lshl_add_u32 v13, v13, 9, v6
	v_lshl_add_u32 v14, v14, 9, v5
	v_lshl_add_u32 v15, v15, 9, v5
	v_lshl_add_u32 v16, v16, 9, v6
	v_lshl_add_u32 v17, v17, 9, v6
	v_lshl_add_u32 v18, v18, 9, v5
	v_lshl_add_u32 v19, v19, 9, v5
	v_lshl_add_u32 v20, v20, 9, v6
	v_lshl_add_u32 v21, v21, 9, v6
	v_lshl_add_u32 v22, v22, 9, v5
	v_lshl_add_u32 v23, v23, 9, v5
	v_lshl_add_u32 v24, v24, 9, v6
	v_lshl_add_u32 v25, v25, 9, v6
	v_lshl_add_u32 v26, v26, 9, v5
	v_lshl_add_u32 v27, v27, 9, v5
	v_lshl_add_u32 v28, v28, 9, v6
	v_lshl_add_u32 v29, v29, 9, v6
	v_lshl_add_u32 v30, v30, 9, v5
	v_lshl_add_u32 v31, v31, 9, v5
	v_lshl_add_u32 v32, v32, 9, v6
	v_lshl_add_u32 v33, v33, 9, v6
	v_lshl_add_u32 v34, v34, 9, v5
	v_lshl_add_u32 v35, v35, 9, v5
	v_lshl_add_u32 v36, v36, 9, v6
	v_lshl_add_u32 v37, v37, 9, v6
	v_lshl_add_u32 v38, v38, 9, v5
	v_lshl_add_u32 v39, v39, 9, v5
	v_lshl_add_u32 v40, v40, 9, v6
	v_lshl_add_u32 v41, v41, 9, v6
	v_lshl_add_u32 v42, v42, 9, v5
	v_lshl_add_u32 v43, v43, 9, v5
	v_lshl_add_u32 v44, v44, 9, v6
	v_lshl_add_u32 v45, v45, 9, v6
	v_lshl_add_u32 v46, v46, 9, v5
	v_lshl_add_u32 v47, v47, 9, v5
	v_lshl_add_u32 v48, v48, 9, v6
	v_lshl_add_u32 v49, v49, 9, v6
	v_lshl_add_u32 v50, v50, 9, v5
	v_lshl_add_u32 v51, v51, 9, v5
	v_lshl_add_u32 v52, v52, 9, v6
	v_lshl_add_u32 v53, v53, 9, v6
	v_lshl_add_u32 v54, v54, 9, v5
	v_lshl_add_u32 v55, v55, 9, v5
	v_lshl_add_u32 v56, v56, 9, v6
	v_lshl_add_u32 v57, v57, 9, v6
	v_lshl_add_u32 v58, v58, 9, v5
	v_lshl_add_u32 v59, v59, 9, v5
	v_lshl_add_u32 v60, v60, 9, v6
	v_lshl_add_u32 v61, v61, 9, v6
	v_lshl_add_u32 v62, v62, 9, v5
	v_lshl_add_u32 v63, v63, 9, v5
	v_lshl_add_u32 v64, v64, 9, v6
	v_lshl_add_u32 v65, v65, 9, v6
	v_lshl_add_u32 v66, v66, 9, v5
	v_lshl_add_u32 v67, v67, 9, v5
	v_lshl_add_u32 v68, v68, 9, v6
	v_lshl_add_u32 v69, v69, 9, v6
	v_lshl_add_u32 v70, v70, 9, v5
	v_lshl_add_u32 v71, v71, 9, v5
	v_lshl_add_u32 v72, v72, 9, v6
	v_lshl_add_u32 v73, v73, 9, v6
	s_add_u32 s0, s50, 0
	s_addc_u32 s1, s51, 0
	s_add_u32 s2, s52, 0
	s_addc_u32 s3, s53, 0
	s_add_u32 s4, s56, 0
	s_addc_u32 s5, s57, 0
	s_add_u32 s6, s58, 0
	s_addc_u32 s7, s59, 0
	global_load_dwordx4 v[92:95], v91, s[4:5] offset:0
	global_load_dwordx4 v[96:99], v91, s[4:5] offset:64
	global_load_dwordx4 v[100:103], v91, s[4:5] offset:128
	global_load_dwordx4 v[104:107], v91, s[4:5] offset:192
	s_add_i32 m0, s75, 0x2400
	s_nop 0
	global_load_lds_dwordx4 v10, s[0:1]
	s_add_i32 m0, s75, 0x2800
	s_nop 0
	global_load_lds_dwordx4 v11, s[0:1]
	s_add_i32 m0, s75, 0x2c00
	s_nop 0
	global_load_lds_dwordx4 v12, s[0:1]
	s_add_i32 m0, s75, 0x3000
	s_nop 0
	global_load_lds_dwordx4 v13, s[0:1]
	s_add_i32 m0, s75, 0x3400
	s_nop 0
	global_load_lds_dwordx4 v14, s[0:1]
	s_add_i32 m0, s75, 0x3800
	s_nop 0
	global_load_lds_dwordx4 v15, s[0:1]
	s_add_i32 m0, s75, 0x3c00
	s_nop 0
	global_load_lds_dwordx4 v16, s[0:1]
	s_add_i32 m0, s75, 0x4000
	s_nop 0
	global_load_lds_dwordx4 v17, s[0:1]
	s_add_i32 m0, s75, 0x1400
	s_nop 0
	global_load_lds_dwordx4 v18, s[0:1]
	s_add_i32 m0, s75, 0x1800
	s_nop 0
	global_load_lds_dwordx4 v19, s[0:1]
	s_add_i32 m0, s75, 0x1c00
	s_nop 0
	global_load_lds_dwordx4 v20, s[0:1]
	s_add_i32 m0, s75, 0x2000
	s_nop 0
	global_load_lds_dwordx4 v21, s[0:1]
	s_add_i32 m0, s75, 0x400
	s_nop 0
	global_load_lds_dwordx4 v22, s[0:1]
	s_add_i32 m0, s75, 0x800
	s_nop 0
	global_load_lds_dwordx4 v23, s[0:1]
	s_add_i32 m0, s75, 0xc00
	s_nop 0
	global_load_lds_dwordx4 v24, s[0:1]
	s_add_i32 m0, s75, 0x1000
	s_nop 0
	global_load_lds_dwordx4 v25, s[0:1]
	s_waitcnt vmcnt(12)
	ds_read_b128 v[108:111], v74 offset:9216
	ds_read_b128 v[112:115], v75 offset:9216
	ds_read_b128 v[116:119], v76 offset:9216
	ds_read_b128 v[120:123], v77 offset:9216
	v_cndmask_b32_e64 v92, 0, v92, s[20:21]
	v_cndmask_b32_e64 v93, 0, v93, s[20:21]
	v_cndmask_b32_e64 v94, 0, v94, s[20:21]
	v_cndmask_b32_e64 v95, 0, v95, s[20:21]
	v_cndmask_b32_e64 v96, 0, v96, s[20:21]
	v_cndmask_b32_e64 v97, 0, v97, s[20:21]
	v_cndmask_b32_e64 v98, 0, v98, s[20:21]
	v_cndmask_b32_e64 v99, 0, v99, s[20:21]
	v_cndmask_b32_e64 v100, 0, v100, s[20:21]
	v_cndmask_b32_e64 v101, 0, v101, s[20:21]
	v_cndmask_b32_e64 v102, 0, v102, s[20:21]
	v_cndmask_b32_e64 v103, 0, v103, s[20:21]
	v_cndmask_b32_e64 v104, 0, v104, s[20:21]
	v_cndmask_b32_e64 v105, 0, v105, s[20:21]
	v_cndmask_b32_e64 v106, 0, v106, s[20:21]
	v_cndmask_b32_e64 v107, 0, v107, s[20:21]
	s_waitcnt lgkmcnt(0)
	v_mfma_f32_16x16x32_bf16 v[140:143], v[92:95], v[108:111], 0
	s_add_i32 m0, s75, 0x2400
	v_mfma_f32_16x16x32_bf16 v[140:143], v[96:99], v[112:115], v[140:143]
	global_load_lds_dwordx4 v26, s[0:1]
	s_add_i32 m0, s75, 0x2800
	v_mfma_f32_16x16x32_bf16 v[140:143], v[100:103], v[116:119], v[140:143]
	global_load_lds_dwordx4 v27, s[0:1]
	s_add_i32 m0, s75, 0x2c00
	v_mfma_f32_16x16x32_bf16 v[140:143], v[104:107], v[120:123], v[140:143]
	global_load_lds_dwordx4 v28, s[0:1]
	s_add_i32 m0, s75, 0x3000
	s_nop 0
	global_load_lds_dwordx4 v29, s[0:1]
	s_waitcnt vmcnt(12)
	ds_read_b128 v[108:111], v74 offset:13312
	ds_read_b128 v[112:115], v75 offset:13312
	ds_read_b128 v[116:119], v76 offset:13312
	ds_read_b128 v[120:123], v77 offset:13312
	s_waitcnt lgkmcnt(0)
	v_mfma_f32_16x16x32_bf16 v[144:147], v[92:95], v[108:111], 0
	s_add_i32 m0, s75, 0x3400
	v_mfma_f32_16x16x32_bf16 v[144:147], v[96:99], v[112:115], v[144:147]
	global_load_lds_dwordx4 v30, s[0:1]
	s_add_i32 m0, s75, 0x3800
	v_mfma_f32_16x16x32_bf16 v[144:147], v[100:103], v[116:119], v[144:147]
	global_load_lds_dwordx4 v31, s[0:1]
	s_add_i32 m0, s75, 0x3c00
	v_mfma_f32_16x16x32_bf16 v[144:147], v[104:107], v[120:123], v[144:147]
	global_load_lds_dwordx4 v32, s[0:1]
	s_add_i32 m0, s75, 0x4000
	s_nop 0
	global_load_lds_dwordx4 v33, s[0:1]
	s_waitcnt vmcnt(12)
	ds_read_b128 v[108:111], v74 offset:5120
	ds_read_b128 v[112:115], v75 offset:5120
	ds_read_b128 v[116:119], v76 offset:5120
	ds_read_b128 v[120:123], v77 offset:5120
	s_waitcnt lgkmcnt(0)
	v_mfma_f32_16x16x32_bf16 v[148:151], v[92:95], v[108:111], 0
	s_add_i32 m0, s75, 0x1400
	v_mfma_f32_16x16x32_bf16 v[148:151], v[96:99], v[112:115], v[148:151]
	global_load_lds_dwordx4 v34, s[0:1]
	s_add_i32 m0, s75, 0x1800
	v_mfma_f32_16x16x32_bf16 v[148:151], v[100:103], v[116:119], v[148:151]
	global_load_lds_dwordx4 v35, s[0:1]
	s_add_i32 m0, s75, 0x1c00
	v_mfma_f32_16x16x32_bf16 v[148:151], v[104:107], v[120:123], v[148:151]
	global_load_lds_dwordx4 v36, s[0:1]
	s_add_i32 m0, s75, 0x2000
	s_nop 0
	global_load_lds_dwordx4 v37, s[0:1]
	s_waitcnt vmcnt(12)
	ds_read_b128 v[108:111], v74 offset:1024
	ds_read_b128 v[112:115], v75 offset:1024
	ds_read_b128 v[116:119], v76 offset:1024
	ds_read_b128 v[120:123], v77 offset:1024
	s_waitcnt lgkmcnt(0)
	v_mfma_f32_16x16x32_bf16 v[152:155], v[92:95], v[108:111], 0
	s_add_i32 m0, s75, 0x400
	v_mfma_f32_16x16x32_bf16 v[152:155], v[96:99], v[112:115], v[152:155]
	global_load_lds_dwordx4 v38, s[0:1]
	s_add_i32 m0, s75, 0x800
	v_mfma_f32_16x16x32_bf16 v[152:155], v[100:103], v[116:119], v[152:155]
	global_load_lds_dwordx4 v39, s[0:1]
	s_add_i32 m0, s75, 0xc00
	v_mfma_f32_16x16x32_bf16 v[152:155], v[104:107], v[120:123], v[152:155]
	global_load_lds_dwordx4 v40, s[0:1]
	s_add_i32 m0, s75, 0x1000
	s_nop 0
	global_load_lds_dwordx4 v41, s[0:1]
	s_waitcnt vmcnt(12)
	ds_read_b128 v[108:111], v74 offset:9216
	ds_read_b128 v[112:115], v75 offset:9216
	ds_read_b128 v[116:119], v76 offset:9216
	ds_read_b128 v[120:123], v77 offset:9216
	s_waitcnt lgkmcnt(0)
	v_mfma_f32_16x16x32_bf16 v[156:159], v[92:95], v[108:111], 0
	s_add_i32 m0, s75, 0x2400
	v_mfma_f32_16x16x32_bf16 v[156:159], v[96:99], v[112:115], v[156:159]
	global_load_lds_dwordx4 v42, s[0:1]
	s_add_i32 m0, s75, 0x2800
	v_mfma_f32_16x16x32_bf16 v[156:159], v[100:103], v[116:119], v[156:159]
	global_load_lds_dwordx4 v43, s[0:1]
	s_add_i32 m0, s75, 0x2c00
	v_mfma_f32_16x16x32_bf16 v[156:159], v[104:107], v[120:123], v[156:159]
	global_load_lds_dwordx4 v44, s[0:1]
	s_add_i32 m0, s75, 0x3000
	s_nop 0
	global_load_lds_dwordx4 v45, s[0:1]
	s_waitcnt vmcnt(12)
	ds_read_b128 v[108:111], v74 offset:13312
	ds_read_b128 v[112:115], v75 offset:13312
	ds_read_b128 v[116:119], v76 offset:13312
	ds_read_b128 v[120:123], v77 offset:13312
	s_waitcnt lgkmcnt(0)
	v_mfma_f32_16x16x32_bf16 v[160:163], v[92:95], v[108:111], 0
	s_add_i32 m0, s75, 0x3400
	v_mfma_f32_16x16x32_bf16 v[160:163], v[96:99], v[112:115], v[160:163]
	global_load_lds_dwordx4 v46, s[0:1]
	s_add_i32 m0, s75, 0x3800
	v_mfma_f32_16x16x32_bf16 v[160:163], v[100:103], v[116:119], v[160:163]
	global_load_lds_dwordx4 v47, s[0:1]
	s_add_i32 m0, s75, 0x3c00
	v_mfma_f32_16x16x32_bf16 v[160:163], v[104:107], v[120:123], v[160:163]
	global_load_lds_dwordx4 v48, s[0:1]
	s_add_i32 m0, s75, 0x4000
	s_nop 0
	global_load_lds_dwordx4 v49, s[0:1]
	s_waitcnt vmcnt(12)
	ds_read_b128 v[108:111], v74 offset:5120
	ds_read_b128 v[112:115], v75 offset:5120
	ds_read_b128 v[116:119], v76 offset:5120
	ds_read_b128 v[120:123], v77 offset:5120
	s_waitcnt lgkmcnt(0)
	v_mfma_f32_16x16x32_bf16 v[164:167], v[92:95], v[108:111], 0
	s_add_i32 m0, s75, 0x1400
	v_mfma_f32_16x16x32_bf16 v[164:167], v[96:99], v[112:115], v[164:167]
	global_load_lds_dwordx4 v50, s[0:1]
	s_add_i32 m0, s75, 0x1800
	v_mfma_f32_16x16x32_bf16 v[164:167], v[100:103], v[116:119], v[164:167]
	global_load_lds_dwordx4 v51, s[0:1]
	s_add_i32 m0, s75, 0x1c00
	v_mfma_f32_16x16x32_bf16 v[164:167], v[104:107], v[120:123], v[164:167]
	global_load_lds_dwordx4 v52, s[0:1]
	s_add_i32 m0, s75, 0x2000
	s_nop 0
	global_load_lds_dwordx4 v53, s[0:1]
	s_waitcnt vmcnt(12)
	ds_read_b128 v[108:111], v74 offset:1024
	ds_read_b128 v[112:115], v75 offset:1024
	ds_read_b128 v[116:119], v76 offset:1024
	ds_read_b128 v[120:123], v77 offset:1024
	s_waitcnt lgkmcnt(0)
	v_mfma_f32_16x16x32_bf16 v[168:171], v[92:95], v[108:111], 0
	s_add_i32 m0, s75, 0x400
	v_mfma_f32_16x16x32_bf16 v[168:171], v[96:99], v[112:115], v[168:171]
	global_load_lds_dwordx4 v54, s[0:1]
	s_add_i32 m0, s75, 0x800
	v_mfma_f32_16x16x32_bf16 v[168:171], v[100:103], v[116:119], v[168:171]
	global_load_lds_dwordx4 v55, s[0:1]
	s_add_i32 m0, s75, 0xc00
	v_mfma_f32_16x16x32_bf16 v[168:171], v[104:107], v[120:123], v[168:171]
	global_load_lds_dwordx4 v56, s[0:1]
	s_add_i32 m0, s75, 0x1000
	s_nop 0
	global_load_lds_dwordx4 v57, s[0:1]
	s_waitcnt vmcnt(12)
	ds_read_b128 v[108:111], v74 offset:9216
	ds_read_b128 v[112:115], v75 offset:9216
	ds_read_b128 v[116:119], v76 offset:9216
	ds_read_b128 v[120:123], v77 offset:9216
	s_waitcnt lgkmcnt(0)
	v_mfma_f32_16x16x32_bf16 v[184:187], v[92:95], v[108:111], 0
	s_add_i32 m0, s75, 0x2400
	v_mfma_f32_16x16x32_bf16 v[184:187], v[96:99], v[112:115], v[184:187]
	global_load_lds_dwordx4 v58, s[0:1]
	s_add_i32 m0, s75, 0x2800
	v_mfma_f32_16x16x32_bf16 v[184:187], v[100:103], v[116:119], v[184:187]
	global_load_lds_dwordx4 v59, s[0:1]
	s_add_i32 m0, s75, 0x2c00
	v_mfma_f32_16x16x32_bf16 v[184:187], v[104:107], v[120:123], v[184:187]
	global_load_lds_dwordx4 v60, s[0:1]
	s_add_i32 m0, s75, 0x3000
	s_nop 0
	global_load_lds_dwordx4 v61, s[0:1]
	s_waitcnt vmcnt(12)
	ds_read_b128 v[108:111], v74 offset:13312
	ds_read_b128 v[112:115], v75 offset:13312
	ds_read_b128 v[116:119], v76 offset:13312
	ds_read_b128 v[120:123], v77 offset:13312
	s_waitcnt lgkmcnt(0)
	v_mfma_f32_16x16x32_bf16 v[188:191], v[92:95], v[108:111], 0
	s_add_i32 m0, s75, 0x3400
	v_mfma_f32_16x16x32_bf16 v[188:191], v[96:99], v[112:115], v[188:191]
	global_load_lds_dwordx4 v62, s[0:1]
	s_add_i32 m0, s75, 0x3800
	v_mfma_f32_16x16x32_bf16 v[188:191], v[100:103], v[116:119], v[188:191]
	global_load_lds_dwordx4 v63, s[0:1]
	s_add_i32 m0, s75, 0x3c00
	v_mfma_f32_16x16x32_bf16 v[188:191], v[104:107], v[120:123], v[188:191]
	global_load_lds_dwordx4 v64, s[0:1]
	s_add_i32 m0, s75, 0x4000
	s_nop 0
	global_load_lds_dwordx4 v65, s[0:1]
	s_waitcnt vmcnt(12)
	ds_read_b128 v[108:111], v74 offset:5120
	ds_read_b128 v[112:115], v75 offset:5120
	ds_read_b128 v[116:119], v76 offset:5120
	ds_read_b128 v[120:123], v77 offset:5120
	s_waitcnt lgkmcnt(0)
	v_mfma_f32_16x16x32_bf16 v[192:195], v[92:95], v[108:111], 0
	s_add_i32 m0, s75, 0x1400
	v_mfma_f32_16x16x32_bf16 v[192:195], v[96:99], v[112:115], v[192:195]
	global_load_lds_dwordx4 v66, s[0:1]
	s_add_i32 m0, s75, 0x1800
	v_mfma_f32_16x16x32_bf16 v[192:195], v[100:103], v[116:119], v[192:195]
	global_load_lds_dwordx4 v67, s[0:1]
	s_add_i32 m0, s75, 0x1c00
	v_mfma_f32_16x16x32_bf16 v[192:195], v[104:107], v[120:123], v[192:195]
	global_load_lds_dwordx4 v68, s[0:1]
	s_add_i32 m0, s75, 0x2000
	s_nop 0
	global_load_lds_dwordx4 v69, s[0:1]
	s_waitcnt vmcnt(12)
	ds_read_b128 v[108:111], v74 offset:1024
	ds_read_b128 v[112:115], v75 offset:1024
	ds_read_b128 v[116:119], v76 offset:1024
	ds_read_b128 v[120:123], v77 offset:1024
	s_waitcnt lgkmcnt(0)
	v_mfma_f32_16x16x32_bf16 v[196:199], v[92:95], v[108:111], 0
	s_add_i32 m0, s75, 0x400
	v_mfma_f32_16x16x32_bf16 v[196:199], v[96:99], v[112:115], v[196:199]
	global_load_lds_dwordx4 v70, s[0:1]
	s_add_i32 m0, s75, 0x800
	v_mfma_f32_16x16x32_bf16 v[196:199], v[100:103], v[116:119], v[196:199]
	global_load_lds_dwordx4 v71, s[0:1]
	s_add_i32 m0, s75, 0xc00
	v_mfma_f32_16x16x32_bf16 v[196:199], v[104:107], v[120:123], v[196:199]
	global_load_lds_dwordx4 v72, s[0:1]
	s_add_i32 m0, s75, 0x1000
	s_nop 0
	global_load_lds_dwordx4 v73, s[0:1]
	s_waitcnt vmcnt(12)
	ds_read_b128 v[108:111], v74 offset:9216
	ds_read_b128 v[112:115], v75 offset:9216
	ds_read_b128 v[116:119], v76 offset:9216
	ds_read_b128 v[120:123], v77 offset:9216
	s_waitcnt lgkmcnt(0)
	v_mfma_f32_16x16x32_bf16 v[200:203], v[92:95], v[108:111], 0
	v_mfma_f32_16x16x32_bf16 v[200:203], v[96:99], v[112:115], v[200:203]
	v_mfma_f32_16x16x32_bf16 v[200:203], v[100:103], v[116:119], v[200:203]
	v_mfma_f32_16x16x32_bf16 v[200:203], v[104:107], v[120:123], v[200:203]
	s_waitcnt vmcnt(8)
	ds_read_b128 v[108:111], v74 offset:13312
	ds_read_b128 v[112:115], v75 offset:13312
	ds_read_b128 v[116:119], v76 offset:13312
	ds_read_b128 v[120:123], v77 offset:13312
	s_waitcnt lgkmcnt(0)
	v_mfma_f32_16x16x32_bf16 v[204:207], v[92:95], v[108:111], 0
	v_mfma_f32_16x16x32_bf16 v[204:207], v[96:99], v[112:115], v[204:207]
	v_mfma_f32_16x16x32_bf16 v[204:207], v[100:103], v[116:119], v[204:207]
	v_mfma_f32_16x16x32_bf16 v[204:207], v[104:107], v[120:123], v[204:207]
	s_waitcnt vmcnt(4)
	ds_read_b128 v[108:111], v74 offset:5120
	ds_read_b128 v[112:115], v75 offset:5120
	ds_read_b128 v[116:119], v76 offset:5120
	ds_read_b128 v[120:123], v77 offset:5120
	s_waitcnt lgkmcnt(0)
	v_mfma_f32_16x16x32_bf16 v[208:211], v[92:95], v[108:111], 0
	v_mfma_f32_16x16x32_bf16 v[208:211], v[96:99], v[112:115], v[208:211]
	v_mfma_f32_16x16x32_bf16 v[208:211], v[100:103], v[116:119], v[208:211]
	v_mfma_f32_16x16x32_bf16 v[208:211], v[104:107], v[120:123], v[208:211]
	s_waitcnt vmcnt(0)
	ds_read_b128 v[108:111], v74 offset:1024
	ds_read_b128 v[112:115], v75 offset:1024
	ds_read_b128 v[116:119], v76 offset:1024
	ds_read_b128 v[120:123], v77 offset:1024
	s_waitcnt lgkmcnt(0)
	v_mfma_f32_16x16x32_bf16 v[212:215], v[92:95], v[108:111], 0
	v_mfma_f32_16x16x32_bf16 v[212:215], v[96:99], v[112:115], v[212:215]
	v_mfma_f32_16x16x32_bf16 v[212:215], v[100:103], v[116:119], v[212:215]
	v_mfma_f32_16x16x32_bf16 v[212:215], v[104:107], v[120:123], v[212:215]
	s_nop 7
	s_mov_b64 exec, 0xffff
	ds_write_b128 v86, v[140:143] offset:1024
	ds_write_b128 v86, v[144:147] offset:1280
	ds_write_b128 v86, v[148:151] offset:1536
	ds_write_b128 v86, v[152:155] offset:1792
	ds_write_b128 v86, v[156:159] offset:2048
	ds_write_b128 v86, v[160:163] offset:2304
	ds_write_b128 v86, v[164:167] offset:2560
	ds_write_b128 v86, v[168:171] offset:2816
	ds_write_b128 v86, v[184:187] offset:3072
	ds_write_b128 v86, v[188:191] offset:3328
	ds_write_b128 v86, v[192:195] offset:3584
	ds_write_b128 v86, v[196:199] offset:3840
	ds_write_b128 v86, v[200:203] offset:4096
	ds_write_b128 v86, v[204:207] offset:4352
	ds_write_b128 v86, v[208:211] offset:4608
	ds_write_b128 v86, v[212:215] offset:4864
	s_mov_b64 exec, -1
	s_add_i32 m0, s75, 0x2400
	s_nop 0
	global_load_lds_dwordx4 v10, s[2:3]
	s_add_i32 m0, s75, 0x2800
	s_nop 0
	global_load_lds_dwordx4 v11, s[2:3]
	s_add_i32 m0, s75, 0x2c00
	s_nop 0
	global_load_lds_dwordx4 v12, s[2:3]
	s_add_i32 m0, s75, 0x3000
	s_nop 0
	global_load_lds_dwordx4 v13, s[2:3]
	s_add_i32 m0, s75, 0x3400
	s_nop 0
	global_load_lds_dwordx4 v14, s[2:3]
	s_add_i32 m0, s75, 0x3800
	s_nop 0
	global_load_lds_dwordx4 v15, s[2:3]
	s_add_i32 m0, s75, 0x3c00
	s_nop 0
	global_load_lds_dwordx4 v16, s[2:3]
	s_add_i32 m0, s75, 0x4000
	s_nop 0
	global_load_lds_dwordx4 v17, s[2:3]
	s_waitcnt lgkmcnt(0)
	ds_read_b128 v[108:111], v87 offset:1024
	ds_read_b128 v[112:115], v87 offset:2048
	ds_read_b128 v[116:119], v87 offset:3072
	ds_read_b128 v[120:123], v87 offset:4096
	s_waitcnt lgkmcnt(0)
	s_add_i32 m0, s75, 0x400
	s_nop 0
	global_load_lds_dwordx4 v18, s[2:3]
	s_add_i32 m0, s75, 0x800
	s_nop 0
	global_load_lds_dwordx4 v19, s[2:3]
	s_add_i32 m0, s75, 0xc00
	s_nop 0
	global_load_lds_dwordx4 v20, s[2:3]
	s_add_i32 m0, s75, 0x1000
	s_nop 0
	global_load_lds_dwordx4 v21, s[2:3]
	s_add_i32 m0, s75, 0x1400
	s_nop 0
	global_load_lds_dwordx4 v22, s[2:3]
	s_add_i32 m0, s75, 0x1800
	s_nop 0
	global_load_lds_dwordx4 v23, s[2:3]
	s_add_i32 m0, s75, 0x1c00
	s_nop 0
	global_load_lds_dwordx4 v24, s[2:3]
	s_add_i32 m0, s75, 0x2000
	s_nop 0
	global_load_lds_dwordx4 v25, s[2:3]
	s_cmp_eq_u32 s73, 0x100
	s_cbranch_scc1 .Lau_nomask1_0
	v_mov_b32_e32 v9, 0xff61b1e6
	v_cndmask_b32_e64 v108, v9, v108, s[24:25]
	v_cndmask_b32_e64 v109, v9, v109, s[24:25]
	v_cndmask_b32_e64 v110, v9, v110, s[24:25]
	v_cndmask_b32_e64 v111, v9, v111, s[24:25]
	v_cndmask_b32_e64 v112, v9, v112, s[26:27]
	v_cndmask_b32_e64 v113, v9, v113, s[26:27]
	v_cndmask_b32_e64 v114, v9, v114, s[26:27]
	v_cndmask_b32_e64 v115, v9, v115, s[26:27]
	v_cndmask_b32_e64 v116, v9, v116, s[28:29]
	v_cndmask_b32_e64 v117, v9, v117, s[28:29]
	v_cndmask_b32_e64 v118, v9, v118, s[28:29]
	v_cndmask_b32_e64 v119, v9, v119, s[28:29]
	v_cndmask_b32_e64 v120, v9, v120, s[30:31]
	v_cndmask_b32_e64 v121, v9, v121, s[30:31]
	v_cndmask_b32_e64 v122, v9, v122, s[30:31]
	v_cndmask_b32_e64 v123, v9, v123, s[30:31]

.Lau_nomask2_0:
	s_nop 0
	v_add_f32_e32 v216, 0, v108
	v_add_f32_e32 v217, 0, v109
	v_add_f32_e32 v218, 0, v110
	v_add_f32_e32 v219, 0, v111
	v_add_f32_e32 v216, v112, v216
	v_add_f32_e32 v217, v113, v217
	v_add_f32_e32 v218, v114, v218
	v_add_f32_e32 v219, v115, v219
	v_add_f32_e32 v216, v116, v216
	v_add_f32_e32 v217, v117, v217
	v_add_f32_e32 v218, v118, v218
	v_add_f32_e32 v219, v119, v219
	v_add_f32_e32 v216, v120, v216
	v_add_f32_e32 v217, v121, v217
	v_add_f32_e32 v218, v122, v218
	v_add_f32_e32 v219, v123, v219
	v_add_f32_dpp v216, v216, v216 quad_perm:[1,0,3,2] row_mask:0xf bank_mask:0xf bound_ctrl:1
	v_add_f32_dpp v217, v217, v217 quad_perm:[1,0,3,2] row_mask:0xf bank_mask:0xf bound_ctrl:1
	v_add_f32_dpp v218, v218, v218 quad_perm:[1,0,3,2] row_mask:0xf bank_mask:0xf bound_ctrl:1
	v_add_f32_dpp v219, v219, v219 quad_perm:[1,0,3,2] row_mask:0xf bank_mask:0xf bound_ctrl:1
	v_add_f32_dpp v216, v216, v216 quad_perm:[2,3,0,1] row_mask:0xf bank_mask:0xf bound_ctrl:1
	v_add_f32_dpp v217, v217, v217 quad_perm:[2,3,0,1] row_mask:0xf bank_mask:0xf bound_ctrl:1
	v_add_f32_dpp v218, v218, v218 quad_perm:[2,3,0,1] row_mask:0xf bank_mask:0xf bound_ctrl:1
	v_add_f32_dpp v219, v219, v219 quad_perm:[2,3,0,1] row_mask:0xf bank_mask:0xf bound_ctrl:1
	v_add_f32_dpp v216, v216, v216 row_half_mirror row_mask:0xf bank_mask:0xf bound_ctrl:1
	v_add_f32_dpp v217, v217, v217 row_half_mirror row_mask:0xf bank_mask:0xf bound_ctrl:1
	v_add_f32_dpp v218, v218, v218 row_half_mirror row_mask:0xf bank_mask:0xf bound_ctrl:1
	v_add_f32_dpp v219, v219, v219 row_half_mirror row_mask:0xf bank_mask:0xf bound_ctrl:1
	v_add_f32_dpp v216, v216, v216 row_mirror row_mask:0xf bank_mask:0xf bound_ctrl:1
	v_add_f32_dpp v217, v217, v217 row_mirror row_mask:0xf bank_mask:0xf bound_ctrl:1
	v_add_f32_dpp v218, v218, v218 row_mirror row_mask:0xf bank_mask:0xf bound_ctrl:1
	v_add_f32_dpp v219, v219, v219 row_mirror row_mask:0xf bank_mask:0xf bound_ctrl:1
	v_add_f32_dpp v216, v216, v216 row_bcast:15 row_mask:0xa bank_mask:0xf
	v_add_f32_dpp v217, v217, v217 row_bcast:15 row_mask:0xa bank_mask:0xf
	v_add_f32_dpp v218, v218, v218 row_bcast:15 row_mask:0xa bank_mask:0xf
	v_add_f32_dpp v219, v219, v219 row_bcast:15 row_mask:0xa bank_mask:0xf
	v_add_f32_dpp v216, v216, v216 row_bcast:31 row_mask:0xc bank_mask:0xf
	v_add_f32_dpp v217, v217, v217 row_bcast:31 row_mask:0xc bank_mask:0xf
	v_add_f32_dpp v218, v218, v218 row_bcast:31 row_mask:0xc bank_mask:0xf
	v_add_f32_dpp v219, v219, v219 row_bcast:31 row_mask:0xc bank_mask:0xf
	s_nop 0
	v_readlane_b32 s84, v216, 63
	v_readlane_b32 s85, v217, 63
	v_readlane_b32 s86, v218, 63
	v_readlane_b32 s87, v219, 63
	s_nop 1
	v_mov_b32_e32 v216, s84
	v_mov_b32_e32 v217, s85
	v_mov_b32_e32 v218, s86
	v_mov_b32_e32 v219, s87
	v_div_scale_f32 v220, s[8:9], v216, v216, 1.0
	v_div_scale_f32 v221, s[8:9], v217, v217, 1.0
	v_div_scale_f32 v222, s[8:9], v218, v218, 1.0
	v_div_scale_f32 v223, s[8:9], v219, v219, 1.0
	v_rcp_f32_e32 v128, v220
	v_rcp_f32_e32 v129, v221
	v_rcp_f32_e32 v130, v222
	v_rcp_f32_e32 v131, v223
	s_nop 0
	v_fma_f32 v124, -v220, v128, 1.0
	v_fma_f32 v125, -v221, v129, 1.0
	v_fma_f32 v126, -v222, v130, 1.0
	v_fma_f32 v127, -v223, v131, 1.0
	v_fmac_f32_e32 v128, v124, v128
	v_fmac_f32_e32 v129, v125, v129
	v_fmac_f32_e32 v130, v126, v130
	v_fmac_f32_e32 v131, v127, v131
	v_div_scale_f32 v224, vcc, 1.0, v216, 1.0
	v_mul_f32_e32 v225, v224, v128
	v_fma_f32 v134, -v220, v225, v224
	v_fmac_f32_e32 v225, v134, v128
	v_fma_f32 v220, -v220, v225, v224
	s_nop 0
	v_div_fmas_f32 v220, v220, v128, v225
	v_div_fixup_f32 v220, v220, v216, 1.0
	v_div_scale_f32 v224, vcc, 1.0, v217, 1.0
	v_mul_f32_e32 v225, v224, v129
	v_fma_f32 v134, -v221, v225, v224
	v_fmac_f32_e32 v225, v134, v129
	v_fma_f32 v221, -v221, v225, v224
	s_nop 0
	v_div_fmas_f32 v221, v221, v129, v225
	v_div_fixup_f32 v221, v221, v217, 1.0
	v_div_scale_f32 v224, vcc, 1.0, v218, 1.0
	v_mul_f32_e32 v225, v224, v130
	v_fma_f32 v134, -v222, v225, v224
	v_fmac_f32_e32 v225, v134, v130
	v_fma_f32 v222, -v222, v225, v224
	s_nop 0
	v_div_fmas_f32 v222, v222, v130, v225
	v_div_fixup_f32 v222, v222, v218, 1.0
	v_div_scale_f32 v224, vcc, 1.0, v219, 1.0
	v_mul_f32_e32 v225, v224, v131
	v_fma_f32 v134, -v223, v225, v224
	v_fmac_f32_e32 v225, v134, v131
	v_fma_f32 v223, -v223, v225, v224
	s_nop 0
	v_div_fmas_f32 v223, v223, v131, v225
	v_div_fixup_f32 v223, v223, v219, 1.0
	v_mul_f32_e32 v108, v108, v220
	v_mul_f32_e32 v109, v109, v221
	v_mul_f32_e32 v110, v110, v222
	v_mul_f32_e32 v111, v111, v223
	v_mul_f32_e32 v112, v112, v220
	v_mul_f32_e32 v113, v113, v221
	v_mul_f32_e32 v114, v114, v222
	v_mul_f32_e32 v115, v115, v223
	v_mul_f32_e32 v116, v116, v220
	v_mul_f32_e32 v117, v117, v221
	v_mul_f32_e32 v118, v118, v222
	v_mul_f32_e32 v119, v119, v223
	v_mul_f32_e32 v120, v120, v220
	v_mul_f32_e32 v121, v121, v221
	v_mul_f32_e32 v122, v122, v222
	v_mul_f32_e32 v123, v123, v223
	v_cvt_pk_bf16_f32 v108, v108, v108
	v_cvt_pk_bf16_f32 v109, v109, v109
	v_cvt_pk_bf16_f32 v110, v110, v110
	v_cvt_pk_bf16_f32 v111, v111, v111
	v_cvt_pk_bf16_f32 v112, v112, v112
	v_cvt_pk_bf16_f32 v113, v113, v113
	v_cvt_pk_bf16_f32 v114, v114, v114
	v_cvt_pk_bf16_f32 v115, v115, v115
	v_cvt_pk_bf16_f32 v116, v116, v116
	v_cvt_pk_bf16_f32 v117, v117, v117
	v_cvt_pk_bf16_f32 v118, v118, v118
	v_cvt_pk_bf16_f32 v119, v119, v119
	v_cvt_pk_bf16_f32 v120, v120, v120
	v_cvt_pk_bf16_f32 v121, v121, v121
	v_cvt_pk_bf16_f32 v122, v122, v122
	v_cvt_pk_bf16_f32 v123, v123, v123
	ds_write_b16 v88, v108 offset:0
	ds_write_b16 v88, v109 offset:512
	ds_write_b16 v88, v110 offset:1024
	ds_write_b16 v88, v111 offset:1536
	ds_write_b16 v88, v112 offset:128
	ds_write_b16 v88, v113 offset:640
	ds_write_b16 v88, v114 offset:1152
	ds_write_b16 v88, v115 offset:1664
	ds_write_b16 v88, v116 offset:256
	ds_write_b16 v88, v117 offset:768
	ds_write_b16 v88, v118 offset:1280
	ds_write_b16 v88, v119 offset:1792
	ds_write_b16 v88, v120 offset:384
	ds_write_b16 v88, v121 offset:896
	ds_write_b16 v88, v122 offset:1408
	ds_write_b16 v88, v123 offset:1920
	s_waitcnt vmcnt(8)
	s_waitcnt lgkmcnt(0)
	ds_read_b128 v[172:175], v89 offset:0
	ds_read_b64_tr_b16 v[140:141], v78 offset:9216
	ds_read_b64_tr_b16 v[142:143], v78 offset:10240
	ds_read_b64_tr_b16 v[144:145], v79 offset:9216
	ds_read_b64_tr_b16 v[146:147], v79 offset:10240
	ds_read_b64_tr_b16 v[148:149], v80 offset:9216
	ds_read_b64_tr_b16 v[150:151], v80 offset:10240
	ds_read_b64_tr_b16 v[152:153], v81 offset:9216
	ds_read_b64_tr_b16 v[154:155], v81 offset:10240
	ds_read_b64_tr_b16 v[156:157], v82 offset:9216
	ds_read_b64_tr_b16 v[158:159], v82 offset:10240
	ds_read_b64_tr_b16 v[160:161], v83 offset:9216
	ds_read_b64_tr_b16 v[162:163], v83 offset:10240
	ds_read_b64_tr_b16 v[164:165], v84 offset:9216
	ds_read_b64_tr_b16 v[166:167], v84 offset:10240
	ds_read_b64_tr_b16 v[168:169], v85 offset:9216
	ds_read_b64_tr_b16 v[170:171], v85 offset:10240
	s_waitcnt lgkmcnt(0)
	v_mfma_f32_16x16x32_bf16 v[184:187], v[172:175], v[140:143], 0
	s_add_i32 m0, s75, 0x2400
	v_mfma_f32_16x16x32_bf16 v[188:191], v[172:175], v[144:147], 0
	global_load_lds_dwordx4 v26, s[2:3]
	s_add_i32 m0, s75, 0x2800
	v_mfma_f32_16x16x32_bf16 v[192:195], v[172:175], v[148:151], 0
	global_load_lds_dwordx4 v27, s[2:3]
	s_add_i32 m0, s75, 0x2c00
	v_mfma_f32_16x16x32_bf16 v[196:199], v[172:175], v[152:155], 0
	global_load_lds_dwordx4 v28, s[2:3]
	s_add_i32 m0, s75, 0x3000
	v_mfma_f32_16x16x32_bf16 v[200:203], v[172:175], v[156:159], 0
	global_load_lds_dwordx4 v29, s[2:3]
	s_add_i32 m0, s75, 0x3400
	v_mfma_f32_16x16x32_bf16 v[204:207], v[172:175], v[160:163], 0
	global_load_lds_dwordx4 v30, s[2:3]
	s_add_i32 m0, s75, 0x3800
	v_mfma_f32_16x16x32_bf16 v[208:211], v[172:175], v[164:167], 0
	global_load_lds_dwordx4 v31, s[2:3]
	s_add_i32 m0, s75, 0x3c00
	v_mfma_f32_16x16x32_bf16 v[212:215], v[172:175], v[168:171], 0
	global_load_lds_dwordx4 v32, s[2:3]
	s_add_i32 m0, s75, 0x4000
	s_nop 0
	global_load_lds_dwordx4 v33, s[2:3]
	s_waitcnt vmcnt(8)
	ds_read_b128 v[172:175], v89 offset:64
	ds_read_b64_tr_b16 v[140:141], v78 offset:1024
	ds_read_b64_tr_b16 v[142:143], v78 offset:2048
	ds_read_b64_tr_b16 v[144:145], v79 offset:1024
	ds_read_b64_tr_b16 v[146:147], v79 offset:2048
	ds_read_b64_tr_b16 v[148:149], v80 offset:1024
	ds_read_b64_tr_b16 v[150:151], v80 offset:2048
	ds_read_b64_tr_b16 v[152:153], v81 offset:1024
	ds_read_b64_tr_b16 v[154:155], v81 offset:2048
	ds_read_b64_tr_b16 v[156:157], v82 offset:1024
	ds_read_b64_tr_b16 v[158:159], v82 offset:2048
	ds_read_b64_tr_b16 v[160:161], v83 offset:1024
	ds_read_b64_tr_b16 v[162:163], v83 offset:2048
	ds_read_b64_tr_b16 v[164:165], v84 offset:1024
	ds_read_b64_tr_b16 v[166:167], v84 offset:2048
	ds_read_b64_tr_b16 v[168:169], v85 offset:1024
	ds_read_b64_tr_b16 v[170:171], v85 offset:2048
	s_waitcnt lgkmcnt(0)
	v_mfma_f32_16x16x32_bf16 v[184:187], v[172:175], v[140:143], v[184:187]
	s_add_i32 m0, s75, 0x400
	v_mfma_f32_16x16x32_bf16 v[188:191], v[172:175], v[144:147], v[188:191]
	global_load_lds_dwordx4 v34, s[2:3]
	s_add_i32 m0, s75, 0x800
	v_mfma_f32_16x16x32_bf16 v[192:195], v[172:175], v[148:151], v[192:195]
	global_load_lds_dwordx4 v35, s[2:3]
	s_add_i32 m0, s75, 0xc00
	v_mfma_f32_16x16x32_bf16 v[196:199], v[172:175], v[152:155], v[196:199]
	global_load_lds_dwordx4 v36, s[2:3]
	s_add_i32 m0, s75, 0x1000
	v_mfma_f32_16x16x32_bf16 v[200:203], v[172:175], v[156:159], v[200:203]
	global_load_lds_dwordx4 v37, s[2:3]
	s_add_i32 m0, s75, 0x1400
	v_mfma_f32_16x16x32_bf16 v[204:207], v[172:175], v[160:163], v[204:207]
	global_load_lds_dwordx4 v38, s[2:3]
	s_add_i32 m0, s75, 0x1800
	v_mfma_f32_16x16x32_bf16 v[208:211], v[172:175], v[164:167], v[208:211]
	global_load_lds_dwordx4 v39, s[2:3]
	s_add_i32 m0, s75, 0x1c00
	v_mfma_f32_16x16x32_bf16 v[212:215], v[172:175], v[168:171], v[212:215]
	global_load_lds_dwordx4 v40, s[2:3]
	s_add_i32 m0, s75, 0x2000
	s_nop 0
	global_load_lds_dwordx4 v41, s[2:3]
	s_waitcnt vmcnt(8)
	ds_read_b128 v[172:175], v89 offset:128
	ds_read_b64_tr_b16 v[140:141], v78 offset:9216
	ds_read_b64_tr_b16 v[142:143], v78 offset:10240
	ds_read_b64_tr_b16 v[144:145], v79 offset:9216
	ds_read_b64_tr_b16 v[146:147], v79 offset:10240
	ds_read_b64_tr_b16 v[148:149], v80 offset:9216
	ds_read_b64_tr_b16 v[150:151], v80 offset:10240
	ds_read_b64_tr_b16 v[152:153], v81 offset:9216
	ds_read_b64_tr_b16 v[154:155], v81 offset:10240
	ds_read_b64_tr_b16 v[156:157], v82 offset:9216
	ds_read_b64_tr_b16 v[158:159], v82 offset:10240
	ds_read_b64_tr_b16 v[160:161], v83 offset:9216
	ds_read_b64_tr_b16 v[162:163], v83 offset:10240
	ds_read_b64_tr_b16 v[164:165], v84 offset:9216
	ds_read_b64_tr_b16 v[166:167], v84 offset:10240
	ds_read_b64_tr_b16 v[168:169], v85 offset:9216
	ds_read_b64_tr_b16 v[170:171], v85 offset:10240
	s_waitcnt lgkmcnt(0)
	v_mfma_f32_16x16x32_bf16 v[184:187], v[172:175], v[140:143], v[184:187]
	s_add_i32 m0, s75, 0x2400
	v_mfma_f32_16x16x32_bf16 v[188:191], v[172:175], v[144:147], v[188:191]
	global_load_lds_dwordx4 v42, s[2:3]
	s_add_i32 m0, s75, 0x2800
	v_mfma_f32_16x16x32_bf16 v[192:195], v[172:175], v[148:151], v[192:195]
	global_load_lds_dwordx4 v43, s[2:3]
	s_add_i32 m0, s75, 0x2c00
	v_mfma_f32_16x16x32_bf16 v[196:199], v[172:175], v[152:155], v[196:199]
	global_load_lds_dwordx4 v44, s[2:3]
	s_add_i32 m0, s75, 0x3000
	v_mfma_f32_16x16x32_bf16 v[200:203], v[172:175], v[156:159], v[200:203]
	global_load_lds_dwordx4 v45, s[2:3]
	s_add_i32 m0, s75, 0x3400
	v_mfma_f32_16x16x32_bf16 v[204:207], v[172:175], v[160:163], v[204:207]
	global_load_lds_dwordx4 v46, s[2:3]
	s_add_i32 m0, s75, 0x3800
	v_mfma_f32_16x16x32_bf16 v[208:211], v[172:175], v[164:167], v[208:211]
	global_load_lds_dwordx4 v47, s[2:3]
	s_add_i32 m0, s75, 0x3c00
	v_mfma_f32_16x16x32_bf16 v[212:215], v[172:175], v[168:171], v[212:215]
	global_load_lds_dwordx4 v48, s[2:3]
	s_add_i32 m0, s75, 0x4000
	s_nop 0
	global_load_lds_dwordx4 v49, s[2:3]
	s_waitcnt vmcnt(8)
	ds_read_b128 v[172:175], v89 offset:192
	ds_read_b64_tr_b16 v[140:141], v78 offset:1024
	ds_read_b64_tr_b16 v[142:143], v78 offset:2048
	ds_read_b64_tr_b16 v[144:145], v79 offset:1024
	ds_read_b64_tr_b16 v[146:147], v79 offset:2048
	ds_read_b64_tr_b16 v[148:149], v80 offset:1024
	ds_read_b64_tr_b16 v[150:151], v80 offset:2048
	ds_read_b64_tr_b16 v[152:153], v81 offset:1024
	ds_read_b64_tr_b16 v[154:155], v81 offset:2048
	ds_read_b64_tr_b16 v[156:157], v82 offset:1024
	ds_read_b64_tr_b16 v[158:159], v82 offset:2048
	ds_read_b64_tr_b16 v[160:161], v83 offset:1024
	ds_read_b64_tr_b16 v[162:163], v83 offset:2048
	ds_read_b64_tr_b16 v[164:165], v84 offset:1024
	ds_read_b64_tr_b16 v[166:167], v84 offset:2048
	ds_read_b64_tr_b16 v[168:169], v85 offset:1024
	ds_read_b64_tr_b16 v[170:171], v85 offset:2048
	s_waitcnt lgkmcnt(0)
	v_mfma_f32_16x16x32_bf16 v[184:187], v[172:175], v[140:143], v[184:187]
	s_add_i32 m0, s75, 0x400
	v_mfma_f32_16x16x32_bf16 v[188:191], v[172:175], v[144:147], v[188:191]
	global_load_lds_dwordx4 v50, s[2:3]
	s_add_i32 m0, s75, 0x800
	v_mfma_f32_16x16x32_bf16 v[192:195], v[172:175], v[148:151], v[192:195]
	global_load_lds_dwordx4 v51, s[2:3]
	s_add_i32 m0, s75, 0xc00
	v_mfma_f32_16x16x32_bf16 v[196:199], v[172:175], v[152:155], v[196:199]
	global_load_lds_dwordx4 v52, s[2:3]
	s_add_i32 m0, s75, 0x1000
	v_mfma_f32_16x16x32_bf16 v[200:203], v[172:175], v[156:159], v[200:203]
	global_load_lds_dwordx4 v53, s[2:3]
	s_add_i32 m0, s75, 0x1400
	v_mfma_f32_16x16x32_bf16 v[204:207], v[172:175], v[160:163], v[204:207]
	global_load_lds_dwordx4 v54, s[2:3]
	s_add_i32 m0, s75, 0x1800
	v_mfma_f32_16x16x32_bf16 v[208:211], v[172:175], v[164:167], v[208:211]
	global_load_lds_dwordx4 v55, s[2:3]
	s_add_i32 m0, s75, 0x1c00
	v_mfma_f32_16x16x32_bf16 v[212:215], v[172:175], v[168:171], v[212:215]
	global_load_lds_dwordx4 v56, s[2:3]
	s_add_i32 m0, s75, 0x2000
	s_nop 0
	global_load_lds_dwordx4 v57, s[2:3]
	s_waitcnt vmcnt(8)
	ds_read_b128 v[172:175], v89 offset:256
	ds_read_b64_tr_b16 v[140:141], v78 offset:9216
	ds_read_b64_tr_b16 v[142:143], v78 offset:10240
	ds_read_b64_tr_b16 v[144:145], v79 offset:9216
	ds_read_b64_tr_b16 v[146:147], v79 offset:10240
	ds_read_b64_tr_b16 v[148:149], v80 offset:9216
	ds_read_b64_tr_b16 v[150:151], v80 offset:10240
	ds_read_b64_tr_b16 v[152:153], v81 offset:9216
	ds_read_b64_tr_b16 v[154:155], v81 offset:10240
	ds_read_b64_tr_b16 v[156:157], v82 offset:9216
	ds_read_b64_tr_b16 v[158:159], v82 offset:10240
	ds_read_b64_tr_b16 v[160:161], v83 offset:9216
	ds_read_b64_tr_b16 v[162:163], v83 offset:10240
	ds_read_b64_tr_b16 v[164:165], v84 offset:9216
	ds_read_b64_tr_b16 v[166:167], v84 offset:10240
	ds_read_b64_tr_b16 v[168:169], v85 offset:9216
	ds_read_b64_tr_b16 v[170:171], v85 offset:10240
	s_waitcnt lgkmcnt(0)
	v_mfma_f32_16x16x32_bf16 v[184:187], v[172:175], v[140:143], v[184:187]
	s_add_i32 m0, s75, 0x2400
	v_mfma_f32_16x16x32_bf16 v[188:191], v[172:175], v[144:147], v[188:191]
	global_load_lds_dwordx4 v58, s[2:3]
	s_add_i32 m0, s75, 0x2800
	v_mfma_f32_16x16x32_bf16 v[192:195], v[172:175], v[148:151], v[192:195]
	global_load_lds_dwordx4 v59, s[2:3]
	s_add_i32 m0, s75, 0x2c00
	v_mfma_f32_16x16x32_bf16 v[196:199], v[172:175], v[152:155], v[196:199]
	global_load_lds_dwordx4 v60, s[2:3]
	s_add_i32 m0, s75, 0x3000
	v_mfma_f32_16x16x32_bf16 v[200:203], v[172:175], v[156:159], v[200:203]
	global_load_lds_dwordx4 v61, s[2:3]
	s_add_i32 m0, s75, 0x3400
	v_mfma_f32_16x16x32_bf16 v[204:207], v[172:175], v[160:163], v[204:207]
	global_load_lds_dwordx4 v62, s[2:3]
	s_add_i32 m0, s75, 0x3800
	v_mfma_f32_16x16x32_bf16 v[208:211], v[172:175], v[164:167], v[208:211]
	global_load_lds_dwordx4 v63, s[2:3]
	s_add_i32 m0, s75, 0x3c00
	v_mfma_f32_16x16x32_bf16 v[212:215], v[172:175], v[168:171], v[212:215]
	global_load_lds_dwordx4 v64, s[2:3]
	s_add_i32 m0, s75, 0x4000
	s_nop 0
	global_load_lds_dwordx4 v65, s[2:3]
	s_waitcnt vmcnt(8)
	ds_read_b128 v[172:175], v89 offset:320
	ds_read_b64_tr_b16 v[140:141], v78 offset:1024
	ds_read_b64_tr_b16 v[142:143], v78 offset:2048
	ds_read_b64_tr_b16 v[144:145], v79 offset:1024
	ds_read_b64_tr_b16 v[146:147], v79 offset:2048
	ds_read_b64_tr_b16 v[148:149], v80 offset:1024
	ds_read_b64_tr_b16 v[150:151], v80 offset:2048
	ds_read_b64_tr_b16 v[152:153], v81 offset:1024
	ds_read_b64_tr_b16 v[154:155], v81 offset:2048
	ds_read_b64_tr_b16 v[156:157], v82 offset:1024
	ds_read_b64_tr_b16 v[158:159], v82 offset:2048
	ds_read_b64_tr_b16 v[160:161], v83 offset:1024
	ds_read_b64_tr_b16 v[162:163], v83 offset:2048
	ds_read_b64_tr_b16 v[164:165], v84 offset:1024
	ds_read_b64_tr_b16 v[166:167], v84 offset:2048
	ds_read_b64_tr_b16 v[168:169], v85 offset:1024
	ds_read_b64_tr_b16 v[170:171], v85 offset:2048
	s_waitcnt lgkmcnt(0)
	v_mfma_f32_16x16x32_bf16 v[184:187], v[172:175], v[140:143], v[184:187]
	s_add_i32 m0, s75, 0x400
	v_mfma_f32_16x16x32_bf16 v[188:191], v[172:175], v[144:147], v[188:191]
	global_load_lds_dwordx4 v66, s[2:3]
	s_add_i32 m0, s75, 0x800
	v_mfma_f32_16x16x32_bf16 v[192:195], v[172:175], v[148:151], v[192:195]
	global_load_lds_dwordx4 v67, s[2:3]
	s_add_i32 m0, s75, 0xc00
	v_mfma_f32_16x16x32_bf16 v[196:199], v[172:175], v[152:155], v[196:199]
	global_load_lds_dwordx4 v68, s[2:3]
	s_add_i32 m0, s75, 0x1000
	v_mfma_f32_16x16x32_bf16 v[200:203], v[172:175], v[156:159], v[200:203]
	global_load_lds_dwordx4 v69, s[2:3]
	s_add_i32 m0, s75, 0x1400
	v_mfma_f32_16x16x32_bf16 v[204:207], v[172:175], v[160:163], v[204:207]
	global_load_lds_dwordx4 v70, s[2:3]
	s_add_i32 m0, s75, 0x1800
	v_mfma_f32_16x16x32_bf16 v[208:211], v[172:175], v[164:167], v[208:211]
	global_load_lds_dwordx4 v71, s[2:3]
	s_add_i32 m0, s75, 0x1c00
	v_mfma_f32_16x16x32_bf16 v[212:215], v[172:175], v[168:171], v[212:215]
	global_load_lds_dwordx4 v72, s[2:3]
	s_add_i32 m0, s75, 0x2000
	s_nop 0
	global_load_lds_dwordx4 v73, s[2:3]
	s_waitcnt vmcnt(8)
	ds_read_b128 v[172:175], v89 offset:384
	ds_read_b64_tr_b16 v[140:141], v78 offset:9216
	ds_read_b64_tr_b16 v[142:143], v78 offset:10240
	ds_read_b64_tr_b16 v[144:145], v79 offset:9216
	ds_read_b64_tr_b16 v[146:147], v79 offset:10240
	ds_read_b64_tr_b16 v[148:149], v80 offset:9216
	ds_read_b64_tr_b16 v[150:151], v80 offset:10240
	ds_read_b64_tr_b16 v[152:153], v81 offset:9216
	ds_read_b64_tr_b16 v[154:155], v81 offset:10240
	ds_read_b64_tr_b16 v[156:157], v82 offset:9216
	ds_read_b64_tr_b16 v[158:159], v82 offset:10240
	ds_read_b64_tr_b16 v[160:161], v83 offset:9216
	ds_read_b64_tr_b16 v[162:163], v83 offset:10240
	ds_read_b64_tr_b16 v[164:165], v84 offset:9216
	ds_read_b64_tr_b16 v[166:167], v84 offset:10240
	ds_read_b64_tr_b16 v[168:169], v85 offset:9216
	ds_read_b64_tr_b16 v[170:171], v85 offset:10240
	s_waitcnt lgkmcnt(0)
	s_add_u32 s0, s0, 0x100
	s_addc_u32 s1, s1, 0
	s_add_u32 s4, s4, 0x400
	s_addc_u32 s5, s5, 0
	global_load_dwordx4 v[92:95], v91, s[4:5] offset:0
	global_load_dwordx4 v[96:99], v91, s[4:5] offset:64
	global_load_dwordx4 v[100:103], v91, s[4:5] offset:128
	global_load_dwordx4 v[104:107], v91, s[4:5] offset:192
	v_mfma_f32_16x16x32_bf16 v[184:187], v[172:175], v[140:143], v[184:187]
	s_add_i32 m0, s75, 0x2400
	v_mfma_f32_16x16x32_bf16 v[188:191], v[172:175], v[144:147], v[188:191]
	global_load_lds_dwordx4 v10, s[0:1]
	s_add_i32 m0, s75, 0x2800
	v_mfma_f32_16x16x32_bf16 v[192:195], v[172:175], v[148:151], v[192:195]
	global_load_lds_dwordx4 v11, s[0:1]
	s_add_i32 m0, s75, 0x2c00
	v_mfma_f32_16x16x32_bf16 v[196:199], v[172:175], v[152:155], v[196:199]
	global_load_lds_dwordx4 v12, s[0:1]
	s_add_i32 m0, s75, 0x3000
	v_mfma_f32_16x16x32_bf16 v[200:203], v[172:175], v[156:159], v[200:203]
	global_load_lds_dwordx4 v13, s[0:1]
	s_add_i32 m0, s75, 0x3400
	v_mfma_f32_16x16x32_bf16 v[204:207], v[172:175], v[160:163], v[204:207]
	global_load_lds_dwordx4 v14, s[0:1]
	s_add_i32 m0, s75, 0x3800
	v_mfma_f32_16x16x32_bf16 v[208:211], v[172:175], v[164:167], v[208:211]
	global_load_lds_dwordx4 v15, s[0:1]
	s_add_i32 m0, s75, 0x3c00
	v_mfma_f32_16x16x32_bf16 v[212:215], v[172:175], v[168:171], v[212:215]
	global_load_lds_dwordx4 v16, s[0:1]
	s_add_i32 m0, s75, 0x4000
	s_nop 0
	global_load_lds_dwordx4 v17, s[0:1]
	s_waitcnt vmcnt(12)
	ds_read_b128 v[172:175], v89 offset:448
	ds_read_b64_tr_b16 v[140:141], v78 offset:1024
	ds_read_b64_tr_b16 v[142:143], v78 offset:2048
	ds_read_b64_tr_b16 v[144:145], v79 offset:1024
	ds_read_b64_tr_b16 v[146:147], v79 offset:2048
	ds_read_b64_tr_b16 v[148:149], v80 offset:1024
	ds_read_b64_tr_b16 v[150:151], v80 offset:2048
	ds_read_b64_tr_b16 v[152:153], v81 offset:1024
	ds_read_b64_tr_b16 v[154:155], v81 offset:2048
	ds_read_b64_tr_b16 v[156:157], v82 offset:1024
	ds_read_b64_tr_b16 v[158:159], v82 offset:2048
	ds_read_b64_tr_b16 v[160:161], v83 offset:1024
	ds_read_b64_tr_b16 v[162:163], v83 offset:2048
	ds_read_b64_tr_b16 v[164:165], v84 offset:1024
	ds_read_b64_tr_b16 v[166:167], v84 offset:2048
	ds_read_b64_tr_b16 v[168:169], v85 offset:1024
	ds_read_b64_tr_b16 v[170:171], v85 offset:2048
	s_waitcnt lgkmcnt(0)
	v_mfma_f32_16x16x32_bf16 v[184:187], v[172:175], v[140:143], v[184:187]
	s_add_i32 m0, s75, 0x1400
	v_mfma_f32_16x16x32_bf16 v[188:191], v[172:175], v[144:147], v[188:191]
	global_load_lds_dwordx4 v18, s[0:1]
	s_add_i32 m0, s75, 0x1800
	v_mfma_f32_16x16x32_bf16 v[192:195], v[172:175], v[148:151], v[192:195]
	global_load_lds_dwordx4 v19, s[0:1]
	s_add_i32 m0, s75, 0x1c00
	v_mfma_f32_16x16x32_bf16 v[196:199], v[172:175], v[152:155], v[196:199]
	global_load_lds_dwordx4 v20, s[0:1]
	s_add_i32 m0, s75, 0x2000
	v_mfma_f32_16x16x32_bf16 v[200:203], v[172:175], v[156:159], v[200:203]
	global_load_lds_dwordx4 v21, s[0:1]
	v_mfma_f32_16x16x32_bf16 v[204:207], v[172:175], v[160:163], v[204:207]
	v_mfma_f32_16x16x32_bf16 v[208:211], v[172:175], v[164:167], v[208:211]
	v_mfma_f32_16x16x32_bf16 v[212:215], v[172:175], v[168:171], v[212:215]
	s_nop 7
	s_mov_b64 exec, 0xffff
	ds_write_b128 v132, v[184:187] offset:0
	ds_write_b128 v132, v[188:191] offset:288
	ds_write_b128 v132, v[192:195] offset:576
	ds_write_b128 v132, v[196:199] offset:864
	ds_write_b128 v132, v[200:203] offset:1152
	ds_write_b128 v132, v[204:207] offset:1440
	ds_write_b128 v132, v[208:211] offset:1728
	ds_write_b128 v132, v[212:215] offset:2016
	s_mov_b64 exec, -1
	s_waitcnt lgkmcnt(0)
	ds_read_b32 v140, v133 offset:0
	ds_read_b32 v141, v133 offset:16
	ds_read_b32 v142, v133 offset:32
	ds_read_b32 v143, v133 offset:48
	ds_read_b32 v144, v133 offset:64
	ds_read_b32 v145, v133 offset:80
	ds_read_b32 v146, v133 offset:96
	ds_read_b32 v147, v133 offset:112
	s_waitcnt lgkmcnt(0)
	v_cvt_pk_bf16_f32 v148, v140, v141
	v_cvt_pk_bf16_f32 v149, v142, v143
	v_cvt_pk_bf16_f32 v150, v144, v145
	v_cvt_pk_bf16_f32 v151, v146, v147
	global_store_dwordx4 v90, v[148:151], s[6:7]
	s_add_u32 s2, s52, 0x100
	s_addc_u32 s3, s53, 0
	s_add_u32 s6, s58, 0x400
	s_addc_u32 s7, s59, 0
	s_add_i32 m0, s75, 0x400
	s_nop 0
	global_load_lds_dwordx4 v22, s[0:1]
	s_add_i32 m0, s75, 0x800
	s_nop 0
	global_load_lds_dwordx4 v23, s[0:1]
	s_add_i32 m0, s75, 0xc00
	s_nop 0
	global_load_lds_dwordx4 v24, s[0:1]
	s_add_i32 m0, s75, 0x1000
	s_nop 0
	global_load_lds_dwordx4 v25, s[0:1]
	s_waitcnt vmcnt(8)
	ds_read_b128 v[108:111], v74 offset:9216
	ds_read_b128 v[112:115], v75 offset:9216
	ds_read_b128 v[116:119], v76 offset:9216
	ds_read_b128 v[120:123], v77 offset:9216
	v_cndmask_b32_e64 v92, 0, v92, s[20:21]
	v_cndmask_b32_e64 v93, 0, v93, s[20:21]
	v_cndmask_b32_e64 v94, 0, v94, s[20:21]
	v_cndmask_b32_e64 v95, 0, v95, s[20:21]
	v_cndmask_b32_e64 v96, 0, v96, s[20:21]
	v_cndmask_b32_e64 v97, 0, v97, s[20:21]
	v_cndmask_b32_e64 v98, 0, v98, s[20:21]
	v_cndmask_b32_e64 v99, 0, v99, s[20:21]
	v_cndmask_b32_e64 v100, 0, v100, s[20:21]
	v_cndmask_b32_e64 v101, 0, v101, s[20:21]
	v_cndmask_b32_e64 v102, 0, v102, s[20:21]
	v_cndmask_b32_e64 v103, 0, v103, s[20:21]
	v_cndmask_b32_e64 v104, 0, v104, s[20:21]
	v_cndmask_b32_e64 v105, 0, v105, s[20:21]
	v_cndmask_b32_e64 v106, 0, v106, s[20:21]
	v_cndmask_b32_e64 v107, 0, v107, s[20:21]
	s_waitcnt lgkmcnt(0)
	v_mfma_f32_16x16x32_bf16 v[140:143], v[92:95], v[108:111], 0
	s_add_i32 m0, s75, 0x2400
	v_mfma_f32_16x16x32_bf16 v[140:143], v[96:99], v[112:115], v[140:143]
	global_load_lds_dwordx4 v26, s[0:1]
	s_add_i32 m0, s75, 0x2800
	v_mfma_f32_16x16x32_bf16 v[140:143], v[100:103], v[116:119], v[140:143]
	global_load_lds_dwordx4 v27, s[0:1]
	s_add_i32 m0, s75, 0x2c00
	v_mfma_f32_16x16x32_bf16 v[140:143], v[104:107], v[120:123], v[140:143]
	global_load_lds_dwordx4 v28, s[0:1]
	s_add_i32 m0, s75, 0x3000
	s_nop 0
	global_load_lds_dwordx4 v29, s[0:1]
	s_waitcnt vmcnt(12)
	ds_read_b128 v[108:111], v74 offset:13312
	ds_read_b128 v[112:115], v75 offset:13312
	ds_read_b128 v[116:119], v76 offset:13312
	ds_read_b128 v[120:123], v77 offset:13312
	s_waitcnt lgkmcnt(0)
	v_mfma_f32_16x16x32_bf16 v[144:147], v[92:95], v[108:111], 0
	s_add_i32 m0, s75, 0x3400
	v_mfma_f32_16x16x32_bf16 v[144:147], v[96:99], v[112:115], v[144:147]
	global_load_lds_dwordx4 v30, s[0:1]
	s_add_i32 m0, s75, 0x3800
	v_mfma_f32_16x16x32_bf16 v[144:147], v[100:103], v[116:119], v[144:147]
	global_load_lds_dwordx4 v31, s[0:1]
	s_add_i32 m0, s75, 0x3c00
	v_mfma_f32_16x16x32_bf16 v[144:147], v[104:107], v[120:123], v[144:147]
	global_load_lds_dwordx4 v32, s[0:1]
	s_add_i32 m0, s75, 0x4000
	s_nop 0
	global_load_lds_dwordx4 v33, s[0:1]
	s_waitcnt vmcnt(12)
	ds_read_b128 v[108:111], v74 offset:5120
	ds_read_b128 v[112:115], v75 offset:5120
	ds_read_b128 v[116:119], v76 offset:5120
	ds_read_b128 v[120:123], v77 offset:5120
	s_waitcnt lgkmcnt(0)
	v_mfma_f32_16x16x32_bf16 v[148:151], v[92:95], v[108:111], 0
	s_add_i32 m0, s75, 0x1400
	v_mfma_f32_16x16x32_bf16 v[148:151], v[96:99], v[112:115], v[148:151]
	global_load_lds_dwordx4 v34, s[0:1]
	s_add_i32 m0, s75, 0x1800
	v_mfma_f32_16x16x32_bf16 v[148:151], v[100:103], v[116:119], v[148:151]
	global_load_lds_dwordx4 v35, s[0:1]
	s_add_i32 m0, s75, 0x1c00
	v_mfma_f32_16x16x32_bf16 v[148:151], v[104:107], v[120:123], v[148:151]
	global_load_lds_dwordx4 v36, s[0:1]
	s_add_i32 m0, s75, 0x2000
	s_nop 0
	global_load_lds_dwordx4 v37, s[0:1]
	s_waitcnt vmcnt(12)
	ds_read_b128 v[108:111], v74 offset:1024
	ds_read_b128 v[112:115], v75 offset:1024
	ds_read_b128 v[116:119], v76 offset:1024
	ds_read_b128 v[120:123], v77 offset:1024
	s_waitcnt lgkmcnt(0)
	v_mfma_f32_16x16x32_bf16 v[152:155], v[92:95], v[108:111], 0
	s_add_i32 m0, s75, 0x400
	v_mfma_f32_16x16x32_bf16 v[152:155], v[96:99], v[112:115], v[152:155]
	global_load_lds_dwordx4 v38, s[0:1]
	s_add_i32 m0, s75, 0x800
	v_mfma_f32_16x16x32_bf16 v[152:155], v[100:103], v[116:119], v[152:155]
	global_load_lds_dwordx4 v39, s[0:1]
	s_add_i32 m0, s75, 0xc00
	v_mfma_f32_16x16x32_bf16 v[152:155], v[104:107], v[120:123], v[152:155]
	global_load_lds_dwordx4 v40, s[0:1]
	s_add_i32 m0, s75, 0x1000
	s_nop 0
	global_load_lds_dwordx4 v41, s[0:1]
	s_waitcnt vmcnt(12)
	ds_read_b128 v[108:111], v74 offset:9216
	ds_read_b128 v[112:115], v75 offset:9216
	ds_read_b128 v[116:119], v76 offset:9216
	ds_read_b128 v[120:123], v77 offset:9216
	s_waitcnt lgkmcnt(0)
	v_mfma_f32_16x16x32_bf16 v[156:159], v[92:95], v[108:111], 0
	s_add_i32 m0, s75, 0x2400
	v_mfma_f32_16x16x32_bf16 v[156:159], v[96:99], v[112:115], v[156:159]
	global_load_lds_dwordx4 v42, s[0:1]
	s_add_i32 m0, s75, 0x2800
	v_mfma_f32_16x16x32_bf16 v[156:159], v[100:103], v[116:119], v[156:159]
	global_load_lds_dwordx4 v43, s[0:1]
	s_add_i32 m0, s75, 0x2c00
	v_mfma_f32_16x16x32_bf16 v[156:159], v[104:107], v[120:123], v[156:159]
	global_load_lds_dwordx4 v44, s[0:1]
	s_add_i32 m0, s75, 0x3000
	s_nop 0
	global_load_lds_dwordx4 v45, s[0:1]
	s_waitcnt vmcnt(12)
	ds_read_b128 v[108:111], v74 offset:13312
	ds_read_b128 v[112:115], v75 offset:13312
	ds_read_b128 v[116:119], v76 offset:13312
	ds_read_b128 v[120:123], v77 offset:13312
	s_waitcnt lgkmcnt(0)
	v_mfma_f32_16x16x32_bf16 v[160:163], v[92:95], v[108:111], 0
	s_add_i32 m0, s75, 0x3400
	v_mfma_f32_16x16x32_bf16 v[160:163], v[96:99], v[112:115], v[160:163]
	global_load_lds_dwordx4 v46, s[0:1]
	s_add_i32 m0, s75, 0x3800
	v_mfma_f32_16x16x32_bf16 v[160:163], v[100:103], v[116:119], v[160:163]
	global_load_lds_dwordx4 v47, s[0:1]
	s_add_i32 m0, s75, 0x3c00
	v_mfma_f32_16x16x32_bf16 v[160:163], v[104:107], v[120:123], v[160:163]
	global_load_lds_dwordx4 v48, s[0:1]
	s_add_i32 m0, s75, 0x4000
	s_nop 0
	global_load_lds_dwordx4 v49, s[0:1]
	s_waitcnt vmcnt(12)
	ds_read_b128 v[108:111], v74 offset:5120
	ds_read_b128 v[112:115], v75 offset:5120
	ds_read_b128 v[116:119], v76 offset:5120
	ds_read_b128 v[120:123], v77 offset:5120
	s_waitcnt lgkmcnt(0)
	v_mfma_f32_16x16x32_bf16 v[164:167], v[92:95], v[108:111], 0
	s_add_i32 m0, s75, 0x1400
	v_mfma_f32_16x16x32_bf16 v[164:167], v[96:99], v[112:115], v[164:167]
	global_load_lds_dwordx4 v50, s[0:1]
	s_add_i32 m0, s75, 0x1800
	v_mfma_f32_16x16x32_bf16 v[164:167], v[100:103], v[116:119], v[164:167]
	global_load_lds_dwordx4 v51, s[0:1]
	s_add_i32 m0, s75, 0x1c00
	v_mfma_f32_16x16x32_bf16 v[164:167], v[104:107], v[120:123], v[164:167]
	global_load_lds_dwordx4 v52, s[0:1]
	s_add_i32 m0, s75, 0x2000
	s_nop 0
	global_load_lds_dwordx4 v53, s[0:1]
	s_waitcnt vmcnt(12)
	ds_read_b128 v[108:111], v74 offset:1024
	ds_read_b128 v[112:115], v75 offset:1024
	ds_read_b128 v[116:119], v76 offset:1024
	ds_read_b128 v[120:123], v77 offset:1024
	s_waitcnt lgkmcnt(0)
	v_mfma_f32_16x16x32_bf16 v[168:171], v[92:95], v[108:111], 0
	s_add_i32 m0, s75, 0x400
	v_mfma_f32_16x16x32_bf16 v[168:171], v[96:99], v[112:115], v[168:171]
	global_load_lds_dwordx4 v54, s[0:1]
	s_add_i32 m0, s75, 0x800
	v_mfma_f32_16x16x32_bf16 v[168:171], v[100:103], v[116:119], v[168:171]
	global_load_lds_dwordx4 v55, s[0:1]
	s_add_i32 m0, s75, 0xc00
	v_mfma_f32_16x16x32_bf16 v[168:171], v[104:107], v[120:123], v[168:171]
	global_load_lds_dwordx4 v56, s[0:1]
	s_add_i32 m0, s75, 0x1000
	s_nop 0
	global_load_lds_dwordx4 v57, s[0:1]
	s_waitcnt vmcnt(12)
	ds_read_b128 v[108:111], v74 offset:9216
	ds_read_b128 v[112:115], v75 offset:9216
	ds_read_b128 v[116:119], v76 offset:9216
	ds_read_b128 v[120:123], v77 offset:9216
	s_waitcnt lgkmcnt(0)
	v_mfma_f32_16x16x32_bf16 v[184:187], v[92:95], v[108:111], 0
	s_add_i32 m0, s75, 0x2400
	v_mfma_f32_16x16x32_bf16 v[184:187], v[96:99], v[112:115], v[184:187]
	global_load_lds_dwordx4 v58, s[0:1]
	s_add_i32 m0, s75, 0x2800
	v_mfma_f32_16x16x32_bf16 v[184:187], v[100:103], v[116:119], v[184:187]
	global_load_lds_dwordx4 v59, s[0:1]
	s_add_i32 m0, s75, 0x2c00
	v_mfma_f32_16x16x32_bf16 v[184:187], v[104:107], v[120:123], v[184:187]
	global_load_lds_dwordx4 v60, s[0:1]
	s_add_i32 m0, s75, 0x3000
	s_nop 0
	global_load_lds_dwordx4 v61, s[0:1]
	s_waitcnt vmcnt(12)
	ds_read_b128 v[108:111], v74 offset:13312
	ds_read_b128 v[112:115], v75 offset:13312
	ds_read_b128 v[116:119], v76 offset:13312
	ds_read_b128 v[120:123], v77 offset:13312
	s_waitcnt lgkmcnt(0)
	v_mfma_f32_16x16x32_bf16 v[188:191], v[92:95], v[108:111], 0
	s_add_i32 m0, s75, 0x3400
	v_mfma_f32_16x16x32_bf16 v[188:191], v[96:99], v[112:115], v[188:191]
	global_load_lds_dwordx4 v62, s[0:1]
	s_add_i32 m0, s75, 0x3800
	v_mfma_f32_16x16x32_bf16 v[188:191], v[100:103], v[116:119], v[188:191]
	global_load_lds_dwordx4 v63, s[0:1]
	s_add_i32 m0, s75, 0x3c00
	v_mfma_f32_16x16x32_bf16 v[188:191], v[104:107], v[120:123], v[188:191]
	global_load_lds_dwordx4 v64, s[0:1]
	s_add_i32 m0, s75, 0x4000
	s_nop 0
	global_load_lds_dwordx4 v65, s[0:1]
	s_waitcnt vmcnt(12)
	ds_read_b128 v[108:111], v74 offset:5120
	ds_read_b128 v[112:115], v75 offset:5120
	ds_read_b128 v[116:119], v76 offset:5120
	ds_read_b128 v[120:123], v77 offset:5120
	s_waitcnt lgkmcnt(0)
	v_mfma_f32_16x16x32_bf16 v[192:195], v[92:95], v[108:111], 0
	s_add_i32 m0, s75, 0x1400
	v_mfma_f32_16x16x32_bf16 v[192:195], v[96:99], v[112:115], v[192:195]
	global_load_lds_dwordx4 v66, s[0:1]
	s_add_i32 m0, s75, 0x1800
	v_mfma_f32_16x16x32_bf16 v[192:195], v[100:103], v[116:119], v[192:195]
	global_load_lds_dwordx4 v67, s[0:1]
	s_add_i32 m0, s75, 0x1c00
	v_mfma_f32_16x16x32_bf16 v[192:195], v[104:107], v[120:123], v[192:195]
	global_load_lds_dwordx4 v68, s[0:1]
	s_add_i32 m0, s75, 0x2000
	s_nop 0
	global_load_lds_dwordx4 v69, s[0:1]
	s_waitcnt vmcnt(12)
	ds_read_b128 v[108:111], v74 offset:1024
	ds_read_b128 v[112:115], v75 offset:1024
	ds_read_b128 v[116:119], v76 offset:1024
	ds_read_b128 v[120:123], v77 offset:1024
	s_waitcnt lgkmcnt(0)
	v_mfma_f32_16x16x32_bf16 v[196:199], v[92:95], v[108:111], 0
	s_add_i32 m0, s75, 0x400
	v_mfma_f32_16x16x32_bf16 v[196:199], v[96:99], v[112:115], v[196:199]
	global_load_lds_dwordx4 v70, s[0:1]
	s_add_i32 m0, s75, 0x800
	v_mfma_f32_16x16x32_bf16 v[196:199], v[100:103], v[116:119], v[196:199]
	global_load_lds_dwordx4 v71, s[0:1]
	s_add_i32 m0, s75, 0xc00
	v_mfma_f32_16x16x32_bf16 v[196:199], v[104:107], v[120:123], v[196:199]
	global_load_lds_dwordx4 v72, s[0:1]
	s_add_i32 m0, s75, 0x1000
	s_nop 0
	global_load_lds_dwordx4 v73, s[0:1]
	s_waitcnt vmcnt(12)
	ds_read_b128 v[108:111], v74 offset:9216
	ds_read_b128 v[112:115], v75 offset:9216
	ds_read_b128 v[116:119], v76 offset:9216
	ds_read_b128 v[120:123], v77 offset:9216
	s_waitcnt lgkmcnt(0)
	v_mfma_f32_16x16x32_bf16 v[200:203], v[92:95], v[108:111], 0
	v_mfma_f32_16x16x32_bf16 v[200:203], v[96:99], v[112:115], v[200:203]
	v_mfma_f32_16x16x32_bf16 v[200:203], v[100:103], v[116:119], v[200:203]
	v_mfma_f32_16x16x32_bf16 v[200:203], v[104:107], v[120:123], v[200:203]
	s_waitcnt vmcnt(8)
	ds_read_b128 v[108:111], v74 offset:13312
	ds_read_b128 v[112:115], v75 offset:13312
	ds_read_b128 v[116:119], v76 offset:13312
	ds_read_b128 v[120:123], v77 offset:13312
	s_waitcnt lgkmcnt(0)
	v_mfma_f32_16x16x32_bf16 v[204:207], v[92:95], v[108:111], 0
	v_mfma_f32_16x16x32_bf16 v[204:207], v[96:99], v[112:115], v[204:207]
	v_mfma_f32_16x16x32_bf16 v[204:207], v[100:103], v[116:119], v[204:207]
	v_mfma_f32_16x16x32_bf16 v[204:207], v[104:107], v[120:123], v[204:207]
	s_waitcnt vmcnt(4)
	ds_read_b128 v[108:111], v74 offset:5120
	ds_read_b128 v[112:115], v75 offset:5120
	ds_read_b128 v[116:119], v76 offset:5120
	ds_read_b128 v[120:123], v77 offset:5120
	s_waitcnt lgkmcnt(0)
	v_mfma_f32_16x16x32_bf16 v[208:211], v[92:95], v[108:111], 0
	v_mfma_f32_16x16x32_bf16 v[208:211], v[96:99], v[112:115], v[208:211]
	v_mfma_f32_16x16x32_bf16 v[208:211], v[100:103], v[116:119], v[208:211]
	v_mfma_f32_16x16x32_bf16 v[208:211], v[104:107], v[120:123], v[208:211]
	s_waitcnt vmcnt(0)
	ds_read_b128 v[108:111], v74 offset:1024
	ds_read_b128 v[112:115], v75 offset:1024
	ds_read_b128 v[116:119], v76 offset:1024
	ds_read_b128 v[120:123], v77 offset:1024
	s_waitcnt lgkmcnt(0)
	v_mfma_f32_16x16x32_bf16 v[212:215], v[92:95], v[108:111], 0
	v_mfma_f32_16x16x32_bf16 v[212:215], v[96:99], v[112:115], v[212:215]
	v_mfma_f32_16x16x32_bf16 v[212:215], v[100:103], v[116:119], v[212:215]
	v_mfma_f32_16x16x32_bf16 v[212:215], v[104:107], v[120:123], v[212:215]
	s_nop 7
	s_mov_b64 exec, 0xffff
	ds_write_b128 v86, v[140:143] offset:1024
	ds_write_b128 v86, v[144:147] offset:1280
	ds_write_b128 v86, v[148:151] offset:1536
	ds_write_b128 v86, v[152:155] offset:1792
	ds_write_b128 v86, v[156:159] offset:2048
	ds_write_b128 v86, v[160:163] offset:2304
	ds_write_b128 v86, v[164:167] offset:2560
	ds_write_b128 v86, v[168:171] offset:2816
	ds_write_b128 v86, v[184:187] offset:3072
	ds_write_b128 v86, v[188:191] offset:3328
	ds_write_b128 v86, v[192:195] offset:3584
	ds_write_b128 v86, v[196:199] offset:3840
	ds_write_b128 v86, v[200:203] offset:4096
	ds_write_b128 v86, v[204:207] offset:4352
	ds_write_b128 v86, v[208:211] offset:4608
	ds_write_b128 v86, v[212:215] offset:4864
	s_mov_b64 exec, -1
	s_add_i32 m0, s75, 0x2400
	s_nop 0
	global_load_lds_dwordx4 v10, s[2:3]
	s_add_i32 m0, s75, 0x2800
	s_nop 0
	global_load_lds_dwordx4 v11, s[2:3]
	s_add_i32 m0, s75, 0x2c00
	s_nop 0
	global_load_lds_dwordx4 v12, s[2:3]
	s_add_i32 m0, s75, 0x3000
	s_nop 0
	global_load_lds_dwordx4 v13, s[2:3]
	s_add_i32 m0, s75, 0x3400
	s_nop 0
	global_load_lds_dwordx4 v14, s[2:3]
	s_add_i32 m0, s75, 0x3800
	s_nop 0
	global_load_lds_dwordx4 v15, s[2:3]
	s_add_i32 m0, s75, 0x3c00
	s_nop 0
	global_load_lds_dwordx4 v16, s[2:3]
	s_add_i32 m0, s75, 0x4000
	s_nop 0
	global_load_lds_dwordx4 v17, s[2:3]
	s_waitcnt lgkmcnt(0)
	ds_read_b128 v[108:111], v87 offset:1024
	ds_read_b128 v[112:115], v87 offset:2048
	ds_read_b128 v[116:119], v87 offset:3072
	ds_read_b128 v[120:123], v87 offset:4096
	s_waitcnt lgkmcnt(0)
	s_add_i32 m0, s75, 0x400
	s_nop 0
	global_load_lds_dwordx4 v18, s[2:3]
	s_add_i32 m0, s75, 0x800
	s_nop 0
	global_load_lds_dwordx4 v19, s[2:3]
	s_add_i32 m0, s75, 0xc00
	s_nop 0
	global_load_lds_dwordx4 v20, s[2:3]
	s_add_i32 m0, s75, 0x1000
	s_nop 0
	global_load_lds_dwordx4 v21, s[2:3]
	s_add_i32 m0, s75, 0x1400
	s_nop 0
	global_load_lds_dwordx4 v22, s[2:3]
	s_add_i32 m0, s75, 0x1800
	s_nop 0
	global_load_lds_dwordx4 v23, s[2:3]
	s_add_i32 m0, s75, 0x1c00
	s_nop 0
	global_load_lds_dwordx4 v24, s[2:3]
	s_add_i32 m0, s75, 0x2000
	s_nop 0
	global_load_lds_dwordx4 v25, s[2:3]
	s_cmp_eq_u32 s73, 0x100
	s_cbranch_scc1 .Lau_nomask1_1
	v_mov_b32_e32 v9, 0xff61b1e6
	v_cndmask_b32_e64 v108, v9, v108, s[24:25]
	v_cndmask_b32_e64 v109, v9, v109, s[24:25]
	v_cndmask_b32_e64 v110, v9, v110, s[24:25]
	v_cndmask_b32_e64 v111, v9, v111, s[24:25]
	v_cndmask_b32_e64 v112, v9, v112, s[26:27]
	v_cndmask_b32_e64 v113, v9, v113, s[26:27]
	v_cndmask_b32_e64 v114, v9, v114, s[26:27]
	v_cndmask_b32_e64 v115, v9, v115, s[26:27]
	v_cndmask_b32_e64 v116, v9, v116, s[28:29]
	v_cndmask_b32_e64 v117, v9, v117, s[28:29]
	v_cndmask_b32_e64 v118, v9, v118, s[28:29]
	v_cndmask_b32_e64 v119, v9, v119, s[28:29]
	v_cndmask_b32_e64 v120, v9, v120, s[30:31]
	v_cndmask_b32_e64 v121, v9, v121, s[30:31]
	v_cndmask_b32_e64 v122, v9, v122, s[30:31]
	v_cndmask_b32_e64 v123, v9, v123, s[30:31]
